# phase 4: FFN2 gate-up weight conversion done only by the 64 HGRN workgroups in their idle time (GEMM workgroups skip it)
# baseline (speedup 1.0000x reference)
; #define LAS __attribute__((address_space(3)))
; __device__ __forceinline__ void p0_items(const Args& a, LAS float* scr, int first, int last, int w, int nw, int lane) {
;     unsigned char* ws = a.ws;
;     auto desc = [&](int it) -> P0Desc {
;         int mi = 0;
; #pragma unroll
;         for (int j = 1; j < 9; ++j) mi += (it >= P0TAB[j].first) ? 1 : 0;
;         const P0Tab t = P0TAB[mi];
;         P0Desc d; d.W = a.in[t.in_w]; d.WT = (bf16*)(ws + t.wt_off); d.gain = t.in_g >= 0 ? a.in[t.in_g] : nullptr; d.scale = t.scale; d.K = t.K; d.N = t.N; d.mode = t.mode; d.item = it - t.first;
;         return d;
;     };
;     float va[32], vb[32]; int it = first + w;
;     P0Desc da = desc(it < last ? it : first), db = da;
;     if (it < last) p0_load(da, va, lane);
; __global__ void __launch_bounds__(NT, 2) hymba_fwd(Args args) {
;     ...
;             for (int qd = bx - GA; qd < 64; qd += G - GA) hg_a2_quad(ws, args.out, lds, qd, tid);
;         }
;     }
;     if (IN(4)) p0_items(args, (LAS float*)(lds + wave * 16384), P0_MID, P0_GU2, gw, NGW, lane);
.LBB0_652:
	s_mul_i32 s98, s3, 3
	s_lshr_b32 s98, s98, 2
	s_sub_i32 s99, s3, s98
	s_lshl_b32 s99, s99, 3
	s_cmp_lt_u32 s2, s98
	s_cbranch_scc1 .Lp4_noconv
	v_readfirstlane_b32 s40, v209
	s_sub_i32 s98, s2, s98
	s_lshl_b32 s98, s98, 3
	s_lshr_b32 s40, s40, 6
	s_add_i32 s98, s98, s40
	s_branch .Lp4_conv
.Lp4_noconv:
	s_movk_i32 s98, 0x4000
.Lp4_conv:
	s_add_i32 s40, s98, 0x2180
	s_cmpk_lt_i32 s98, 0xb00
	s_cselect_b64 s[4:5], -1, 0
	s_and_b64 s[6:7], s[4:5], exec
	s_cselect_b32 s8, s40, 0x2180
	s_cmpk_gt_i32 s8, 0xaff
	s_cselect_b64 s[6:7], -1, 0
	s_cmpk_gt_i32 s8, 0xeff
	v_cndmask_b32_e64 v0, 0, 1, s[6:7]
	s_cselect_b64 s[6:7], -1, 0
	s_cmpk_gt_i32 s8, 0x147f
	s_waitcnt lgkmcnt(0)
	v_cndmask_b32_e64 v1, 0, 1, s[6:7]
	s_cselect_b64 s[6:7], -1, 0
	v_readfirstlane_b32 s9, v0
	v_readfirstlane_b32 s10, v1
	s_cmp_lg_u64 s[6:7], 0
	s_addc_u32 s9, s9, s10
	s_cmpk_gt_i32 s8, 0x1b7f
	s_cselect_b64 s[6:7], -1, 0
	v_cndmask_b32_e64 v0, 0, 1, s[6:7]
	s_mov_b64 s[26:27], 0
	v_readfirstlane_b32 s6, v0
	s_add_u32 s9, s9, s6
	s_addc_u32 s10, 0, 0
	s_cmpk_gt_i32 s8, 0x1d7f
	s_cselect_b64 s[6:7], -1, 0
	v_cndmask_b32_e64 v0, 0, 1, s[6:7]
	s_nop 0
	v_readfirstlane_b32 s6, v0
	s_add_u32 s9, s9, s6
	s_addc_u32 s10, s10, 0
	s_cmpk_gt_i32 s8, 0x1f7f
	s_cselect_b64 s[6:7], -1, 0
	v_cndmask_b32_e64 v0, 0, 1, s[6:7]
	s_nop 0
	v_readfirstlane_b32 s6, v0
	s_add_u32 s9, s9, s6
	s_addc_u32 s10, s10, 0
	s_cmpk_gt_i32 s8, 0x217f
	s_cselect_b64 s[6:7], -1, 0
	v_cndmask_b32_e64 v0, 0, 1, s[6:7]
	s_nop 0
	v_readfirstlane_b32 s6, v0
	s_add_u32 s9, s9, s6
	s_addc_u32 s10, s10, 0
	s_cmpk_gt_i32 s8, 0x2c7f
	s_cselect_b64 s[6:7], -1, 0
	v_cndmask_b32_e64 v0, 0, 1, s[6:7]
	s_nop 0
	v_readfirstlane_b32 s6, v0
	s_add_u32 s8, s9, s6
	s_addc_u32 s6, s10, 0
	s_mul_i32 s6, s6, 40
	s_mul_hi_u32 s7, s8, 40
	s_add_i32 s18, s7, s6
	s_mul_i32 s19, s8, 40
	s_getpc_b64 s[6:7]
	s_add_u32 s6, s6, _ZL5P0TAB@rel32@lo+4
	s_addc_u32 s7, s7, _ZL5P0TAB@rel32@hi+12
	s_add_u32 s6, s6, s19
	s_addc_u32 s7, s7, s18
	s_load_dword s10, s[6:7], 0x0
	s_mov_b32 s9, 0
	s_waitcnt lgkmcnt(0)
	s_ashr_i32 s11, s10, 31
	s_getpc_b64 s[12:13]
	s_add_u32 s12, s12, _ZL5P0TAB@rel32@lo+12
	s_addc_u32 s13, s13, _ZL5P0TAB@rel32@hi+20
	s_add_u32 s12, s12, s19
	s_addc_u32 s13, s13, s18
	s_getpc_b64 s[16:17]
	s_add_u32 s16, s16, _ZL5P0TAB@rel32@lo+36
	s_addc_u32 s17, s17, _ZL5P0TAB@rel32@hi+44
	s_add_u32 s16, s16, s19
	s_addc_u32 s17, s17, s18
	s_lshl_b64 s[10:11], s[10:11], 3
	s_add_u32 s10, s0, s10
	s_addc_u32 s11, s1, s11
	s_lshl_b64 s[18:19], 1, s8
	s_and_b32 s8, s18, 0xa9
	s_cmp_eq_u64 s[8:9], 0
	s_cbranch_scc1 .LBB0_654
	s_load_dword s8, s[6:7], 0x4
	s_waitcnt lgkmcnt(0)
	s_lshl_b64 s[6:7], s[8:9], 3
	s_add_u32 s6, s0, s6
	s_addc_u32 s7, s1, s7
	s_load_dwordx2 s[26:27], s[6:7], 0x0
.LBB0_654:
	s_andn2_b64 vcc, exec, s[4:5]
	s_cbranch_vccnz .LBB0_689
	s_load_dwordx4 s[4:7], s[12:13], 0x0
	s_load_dwordx2 s[20:21], s[0:1], 0xb0
	s_load_dwordx2 s[18:19], s[16:17], 0x0
	s_load_dword s8, s[12:13], 0x10
	s_lshl_b32 s9, s88, 14
	s_add_i32 s9, s9, 0
	s_waitcnt lgkmcnt(0)
	s_sub_i32 s7, s40, s7
	s_add_u32 s28, s20, s18
	s_addc_u32 s29, s21, s19
	s_ashr_i32 s13, s5, 31
	s_lshr_b32 s12, s13, 27
	s_add_i32 s12, s5, s12
	s_ashr_i32 s12, s12, 5
	s_abs_i32 s16, s12
	v_cvt_f32_u32_e32 v0, s16
	s_sub_i32 s19, 0, s16
	s_abs_i32 s17, s7
	s_xor_b32 s18, s7, s12
	v_rcp_iflag_f32_e32 v0, v0
	s_ashr_i32 s18, s18, 31
	s_load_dwordx2 s[10:11], s[10:11], 0x0
	v_lshrrev_b32_e32 v39, 5, v208
	v_mul_f32_e32 v0, 0x4f7ffffe, v0
	v_cvt_u32_f32_e32 v0, v0
	v_and_b32_e32 v38, 31, v209
	v_mov_b32_e32 v41, 0
	v_lshlrev_b32_e32 v40, 2, v38
	v_readfirstlane_b32 s22, v0
	s_mul_i32 s19, s19, s22
	s_mul_hi_u32 s19, s22, s19
	s_add_i32 s22, s22, s19
	s_mul_hi_u32 s19, s17, s22
	s_mul_i32 s22, s19, s16
	s_sub_i32 s17, s17, s22
	s_add_i32 s25, s19, 1
	s_sub_i32 s22, s17, s16
	s_cmp_ge_u32 s17, s16
	s_cselect_b32 s19, s25, s19
	s_cselect_b32 s17, s22, s17
	s_add_i32 s22, s19, 1
	s_cmp_ge_u32 s17, s16
	s_cselect_b32 s16, s22, s19
	s_xor_b32 s16, s16, s18
	s_sub_i32 s17, s16, s18
	s_mul_i32 s12, s17, s12
	s_sub_i32 s12, s7, s12
	v_lshl_or_b32 v0, s17, 6, v39
	s_lshl_b32 s16, s12, 5
	v_mad_i64_i32 v[0:1], s[18:19], v0, s5, 0
	s_waitcnt lgkmcnt(0)
	v_lshl_add_u64 v[0:1], v[0:1], 2, s[10:11]
	s_ashr_i32 s17, s16, 31
	s_mov_b32 s12, s5
	v_lshl_add_u64 v[0:1], s[16:17], 2, v[0:1]
	v_lshl_add_u64 v[0:1], v[0:1], 0, v[40:41]
	s_lshl_b64 s[10:11], s[12:13], 3
	v_lshl_add_u64 v[16:17], v[0:1], 0, s[10:11]
	v_lshl_add_u64 v[18:19], v[16:17], 0, s[10:11]
	v_lshl_add_u64 v[20:21], v[18:19], 0, s[10:11]
	v_lshl_add_u64 v[22:23], v[20:21], 0, s[10:11]
	v_lshl_add_u64 v[24:25], v[22:23], 0, s[10:11]
	v_lshl_add_u64 v[26:27], v[24:25], 0, s[10:11]
	v_lshl_add_u64 v[28:29], v[26:27], 0, s[10:11]
	v_lshl_add_u64 v[30:31], v[28:29], 0, s[10:11]
	v_lshl_add_u64 v[32:33], v[30:31], 0, s[10:11]
	v_lshl_add_u64 v[34:35], v[32:33], 0, s[10:11]
	v_lshl_add_u64 v[36:37], v[34:35], 0, s[10:11]
	v_lshl_add_u64 v[44:45], v[36:37], 0, s[10:11]
	v_lshl_add_u64 v[84:85], v[44:45], 0, s[10:11]
	v_lshl_add_u64 v[86:87], v[84:85], 0, s[10:11]
	v_lshl_add_u64 v[88:89], v[86:87], 0, s[10:11]
	v_lshl_add_u64 v[90:91], v[88:89], 0, s[10:11]
	v_lshl_add_u64 v[92:93], v[90:91], 0, s[10:11]
	v_lshl_add_u64 v[94:95], v[92:93], 0, s[10:11]
	v_lshl_add_u64 v[96:97], v[94:95], 0, s[10:11]
	v_lshl_add_u64 v[98:99], v[96:97], 0, s[10:11]
	v_lshl_add_u64 v[100:101], v[98:99], 0, s[10:11]
	v_lshl_add_u64 v[102:103], v[100:101], 0, s[10:11]
	v_lshl_add_u64 v[104:105], v[102:103], 0, s[10:11]
	v_lshl_add_u64 v[106:107], v[104:105], 0, s[10:11]
	v_lshl_add_u64 v[108:109], v[106:107], 0, s[10:11]
; #define LAS __attribute__((address_space(3)))
; __device__ __forceinline__ unsigned pk2(float lo, float hi) { return pg8::cvt_pk_bf16(lo, hi); }
; #define LDS_WAIT() asm volatile("s_waitcnt lgkmcnt(0)" ::: "memory")
; __device__ __forceinline__ void p0_load(const P0Desc& d, float (&v)[32], int lane) {
;     const int nblk = d.N / 32, kb = d.item / nblk, nb = d.item % nblk, k0 = 64 * kb, n0 = 32 * nb;
;     const float* p = d.W + (size_t)(k0 + (lane >> 5)) * d.N + n0 + (lane & 31);
; #pragma unroll
;     for (int i = 0; i < 32; ++i) v[i] = __builtin_nontemporal_load(p + (size_t)(2 * i) * d.N);
; }
; __device__ __forceinline__ void p0_store(const P0Desc& d, const float (&v)[32], LAS float* scr, int lane) {
;     const int nblk = d.N / 32, kb = d.item / nblk, nb = d.item % nblk, k0 = 64 * kb, n0 = 32 * nb;
; #pragma unroll
;     for (int i = 0; i < 32; ++i) scr[(2 * i + (lane >> 5)) * 33 + (lane & 31)] = v[i];
;     LDS_WAIT(); asm volatile("" ::: "memory");
;     const int c = lane & 7; const int r0 = rowmap(d.mode, n0, d.N);
;     f32x4 g0 = {d.scale, d.scale, d.scale, d.scale}, g1 = g0;
;     if (d.gain) { g0 = *(const f32x4*)(d.gain + k0 + 8 * c) * d.scale; g1 = *(const f32x4*)(d.gain + k0 + 8 * c + 4) * d.scale; }
; #pragma unroll
;     for (int j = 0; j < 4; ++j) { const int n = (lane >> 3) + 8 * j; const LAS float* q = scr + (8 * c) * 33 + n;
;         v4u o; o.x = pk2(q[0 * 33] * g0[0], q[1 * 33] * g0[1]); o.y = pk2(q[2 * 33] * g0[2], q[3 * 33] * g0[3]); o.z = pk2(q[4 * 33] * g1[0], q[5 * 33] * g1[1]); o.w = pk2(q[6 * 33] * g1[2], q[7 * 33] * g1[3]);
;         pg8::st_wt16(d.WT + (size_t)(r0 + n) * d.K + k0 + 8 * c, o); }
;     LDS_WAIT(); asm volatile("" ::: "memory");
; __device__ __forceinline__ void p0_items(const Args& a, LAS float* scr, int first, int last, int w, int nw, int lane) {
;     ...
;     while (it < last) {
;         const int n1 = it + nw; if (n1 < last) { db = desc(n1); p0_load(db, vb, lane); }
;         p0_store(da, va, scr, lane);
;         if (n1 >= last) break;
;         const int n2 = n1 + nw; if (n2 < last) { da = desc(n2); p0_load(da, va, lane); }
;         p0_store(db, vb, scr, lane);
;         it = n2;
;     }
	v_lshl_add_u64 v[110:111], v[108:109], 0, s[10:11]
	v_lshl_add_u64 v[112:113], v[110:111], 0, s[10:11]
	v_lshl_add_u64 v[114:115], v[112:113], 0, s[10:11]
	v_lshl_add_u64 v[116:117], v[114:115], 0, s[10:11]
	v_and_b32_e32 v4, 7, v209
	v_lshrrev_b32_e32 v43, 3, v208
	v_lshl_add_u64 v[118:119], v[116:117], 0, s[10:11]
	v_add_u32_e32 v2, s9, v40
	v_mul_u32_u24_e32 v3, 0x84, v39
	v_lshlrev_b32_e32 v42, 3, v4
	v_mul_u32_u24_e32 v4, 0x420, v4
	v_lshlrev_b32_e32 v5, 2, v43
	v_lshl_add_u64 v[120:121], v[118:119], 0, s[10:11]
	v_add3_u32 v46, s9, v4, v5
	v_add_u32_e32 v50, v2, v3
	global_load_dword v0, v[0:1], off nt
	s_nop 0
	global_load_dword v1, v[16:17], off nt
	global_load_dword v2, v[18:19], off nt
	global_load_dword v3, v[20:21], off nt
	global_load_dword v4, v[22:23], off nt
	global_load_dword v5, v[24:25], off nt
	global_load_dword v6, v[26:27], off nt
	global_load_dword v7, v[28:29], off nt
	global_load_dword v8, v[30:31], off nt
	global_load_dword v9, v[32:33], off nt
	global_load_dword v10, v[34:35], off nt
	global_load_dword v11, v[36:37], off nt
	global_load_dword v12, v[44:45], off nt
	global_load_dword v13, v[84:85], off nt
	global_load_dword v14, v[86:87], off nt
	global_load_dword v15, v[88:89], off nt
	global_load_dword v16, v[90:91], off nt
	global_load_dword v17, v[92:93], off nt
	global_load_dword v18, v[94:95], off nt
	global_load_dword v19, v[96:97], off nt
	global_load_dword v20, v[98:99], off nt
	global_load_dword v21, v[100:101], off nt
	global_load_dword v22, v[102:103], off nt
	global_load_dword v23, v[104:105], off nt
	global_load_dword v24, v[106:107], off nt
	global_load_dword v25, v[108:109], off nt
	global_load_dword v26, v[110:111], off nt
	global_load_dword v27, v[112:113], off nt
	global_load_dword v28, v[114:115], off nt
	global_load_dword v29, v[116:117], off nt
	global_load_dword v30, v[118:119], off nt
	global_load_dword v31, v[120:121], off nt
	s_mov_b32 s23, 0
	v_or_b32_e32 v47, 8, v43
	v_or_b32_e32 v48, 16, v43
	v_or_b32_e32 v49, 24, v43
	s_lshl_b32 s25, s99, 1
	v_lshlrev_b32_e32 v40, 1, v42
	s_mov_b64 s[34:35], s[28:29]
	s_mov_b64 s[30:31], s[26:27]
	s_mov_b32 s19, s7
	s_mov_b32 s12, s8
	s_mov_b32 s13, s4
	s_mov_b32 s17, s5
	s_mov_b32 s18, s6
	s_branch .LBB0_658
.LBB0_656:
	ds_read2_b32 v[88:89], v46 offset1:8
	ds_read2_b32 v[90:91], v46 offset0:33 offset1:41
	ds_read2_b32 v[92:93], v46 offset0:66 offset1:74
	ds_read2_b32 v[94:95], v46 offset0:99 offset1:107
	ds_read2_b32 v[96:97], v46 offset0:132 offset1:140
	ds_read2_b32 v[98:99], v46 offset0:165 offset1:173
	ds_read2_b32 v[100:101], v46 offset0:198 offset1:206
	ds_read2_b32 v[102:103], v46 offset0:231 offset1:239
	s_waitcnt lgkmcnt(7)
	v_mov_b32_e32 v84, v88
	s_waitcnt lgkmcnt(6)
	v_mov_b32_e32 v85, v90
	s_waitcnt lgkmcnt(5)
	v_mov_b32_e32 v86, v92
	s_waitcnt lgkmcnt(4)
	v_mov_b32_e32 v87, v94
	v_pk_mul_f32 v[84:85], v[34:35], v[84:85]
	v_pk_mul_f32 v[86:87], v[44:45], v[86:87]
	v_cvt_pk_bf16_f32 v84, v84, v85
	v_cvt_pk_bf16_f32 v85, v86, v87
	v_mov_b32_e32 v33, v83
	s_waitcnt lgkmcnt(3)
	v_mov_b32_e32 v86, v96
	s_waitcnt lgkmcnt(2)
	v_mov_b32_e32 v87, v98
	s_waitcnt lgkmcnt(1)
	v_mov_b32_e32 v104, v100
	s_waitcnt lgkmcnt(0)
	v_mov_b32_e32 v105, v102
	v_pk_mul_f32 v[86:87], v[32:33], v[86:87]
	v_pk_mul_f32 v[104:105], v[36:37], v[104:105]
	v_add_u32_e32 v83, s16, v43
	v_cvt_pk_bf16_f32 v86, v86, v87
	v_cvt_pk_bf16_f32 v87, v104, v105
	v_mad_i64_i32 v[104:105], s[10:11], v83, s9, 0
	v_lshl_add_u64 v[104:105], v[104:105], 1, s[28:29]
	s_lshl_b64 s[10:11], s[36:37], 1
	v_lshl_add_u64 v[104:105], v[104:105], 0, s[10:11]
	v_lshl_add_u64 v[104:105], v[104:105], 0, v[40:41]
	v_mov_b32_e32 v90, v89
	v_mov_b32_e32 v94, v93
	global_store_dwordx4 v[104:105], v[84:87], off
	v_mov_b32_e32 v98, v97
	v_mov_b32_e32 v102, v101
	v_pk_mul_f32 v[84:85], v[34:35], v[90:91]
	v_pk_mul_f32 v[86:87], v[44:45], v[94:95]
	v_cvt_pk_bf16_f32 v84, v84, v85
	v_cvt_pk_bf16_f32 v85, v86, v87
	v_pk_mul_f32 v[86:87], v[32:33], v[98:99]
	v_pk_mul_f32 v[88:89], v[36:37], v[102:103]
	v_add_u32_e32 v83, s16, v47
	v_cvt_pk_bf16_f32 v86, v86, v87
	v_cvt_pk_bf16_f32 v87, v88, v89
	v_mad_i64_i32 v[88:89], s[36:37], v83, s9, 0
	v_lshl_add_u64 v[88:89], v[88:89], 1, s[28:29]
	v_lshl_add_u64 v[88:89], v[88:89], 0, s[10:11]
	v_lshl_add_u64 v[88:89], v[88:89], 0, v[40:41]
	ds_read2_b32 v[90:91], v46 offset0:16 offset1:24
	ds_read2_b32 v[92:93], v46 offset0:49 offset1:57
	global_store_dwordx4 v[88:89], v[84:87], off
	ds_read2_b32 v[88:89], v46 offset0:82 offset1:90
	ds_read2_b32 v[94:95], v46 offset0:115 offset1:123
	ds_read2_b32 v[96:97], v46 offset0:148 offset1:156
	ds_read2_b32 v[98:99], v46 offset0:181 offset1:189
	ds_read2_b32 v[100:101], v46 offset0:214 offset1:222
	ds_read2_b32 v[102:103], v46 offset0:247 offset1:255
	s_waitcnt lgkmcnt(7)
	v_mov_b32_e32 v84, v90
	s_waitcnt lgkmcnt(6)
	v_mov_b32_e32 v85, v92
	s_waitcnt lgkmcnt(5)
	v_mov_b32_e32 v86, v88
	s_waitcnt lgkmcnt(4)
	v_mov_b32_e32 v87, v94
	v_pk_mul_f32 v[84:85], v[34:35], v[84:85]
	v_pk_mul_f32 v[86:87], v[44:45], v[86:87]
	v_cvt_pk_bf16_f32 v84, v84, v85
	v_cvt_pk_bf16_f32 v85, v86, v87
	s_waitcnt lgkmcnt(3)
	v_mov_b32_e32 v86, v96
	s_waitcnt lgkmcnt(2)
	v_mov_b32_e32 v87, v98
	s_waitcnt lgkmcnt(1)
	v_mov_b32_e32 v104, v100
	s_waitcnt lgkmcnt(0)
	v_mov_b32_e32 v105, v102
	v_pk_mul_f32 v[86:87], v[32:33], v[86:87]
	v_pk_mul_f32 v[104:105], v[36:37], v[104:105]
	v_add_u32_e32 v83, s16, v48
	v_cvt_pk_bf16_f32 v86, v86, v87
	v_cvt_pk_bf16_f32 v87, v104, v105
	v_mad_i64_i32 v[104:105], s[36:37], v83, s9, 0
	v_lshl_add_u64 v[104:105], v[104:105], 1, s[28:29]
	v_lshl_add_u64 v[104:105], v[104:105], 0, s[10:11]
	v_mov_b32_e32 v98, v97
	v_lshl_add_u64 v[104:105], v[104:105], 0, v[40:41]
	v_pk_mul_f32 v[32:33], v[32:33], v[98:99]
	v_mov_b32_e32 v102, v101
	global_store_dwordx4 v[104:105], v[84:87], off
	v_mov_b32_e32 v92, v91
	v_pk_mul_f32 v[34:35], v[34:35], v[92:93]
	v_cvt_pk_bf16_f32 v86, v32, v33
	v_pk_mul_f32 v[32:33], v[36:37], v[102:103]
	v_mov_b32_e32 v94, v89
	v_cvt_pk_bf16_f32 v87, v32, v33
	v_add_u32_e32 v32, s16, v49
	v_mad_i64_i32 v[32:33], s[36:37], v32, s9, 0
	v_lshl_add_u64 v[32:33], v[32:33], 1, s[28:29]
	v_cvt_pk_bf16_f32 v84, v34, v35
	v_pk_mul_f32 v[34:35], v[44:45], v[94:95]
	v_lshl_add_u64 v[32:33], v[32:33], 0, s[10:11]
	v_cvt_pk_bf16_f32 v85, v34, v35
	v_lshl_add_u64 v[32:33], v[32:33], 0, v[40:41]
	global_store_dwordx4 v[32:33], v[84:87], off
	s_waitcnt lgkmcnt(0)
	s_add_i32 s40, s41, s99
	s_cmpk_gt_i32 s40, 0x2c7f
	s_cselect_b64 s[36:37], -1, 0

; __device__ __forceinline__ void p0_items(const Args& a, LAS float* scr, int first, int last, int w, int nw, int lane) {
;     ...
;     auto desc = [&](int it) -> P0Desc {
;         int mi = 0;
; #pragma unroll
;         for (int j = 1; j < 9; ++j) mi += (it >= P0TAB[j].first) ? 1 : 0;
;         const P0Tab t = P0TAB[mi];
;         P0Desc d; d.W = a.in[t.in_w]; d.WT = (bf16*)(ws + t.wt_off); d.gain = t.in_g >= 0 ? a.in[t.in_g] : nullptr; d.scale = t.scale; d.K = t.K; d.N = t.N; d.mode = t.mode; d.item = it - t.first;
;         return d;
;     ...
;     while (it < last) {
;         const int n1 = it + nw; if (n1 < last) { db = desc(n1); p0_load(db, vb, lane); }
;         p0_store(da, va, scr, lane);
;         if (n1 >= last) break;
;         const int n2 = n1 + nw; if (n2 < last) { da = desc(n2); p0_load(da, va, lane); }
.LBB0_658:
	s_add_i32 s41, s40, s99
	s_cmpk_lt_i32 s41, 0x2c80
	s_cselect_b64 s[36:37], -1, 0
	s_cmpk_gt_i32 s41, 0x2c7f
	s_cbranch_scc1 .LBB0_662
	s_cmpk_gt_i32 s41, 0xaff
	s_cselect_b64 s[4:5], -1, 0
	s_cmpk_gt_i32 s41, 0xeff
	v_cndmask_b32_e64 v32, 0, 1, s[4:5]
	s_cselect_b64 s[4:5], -1, 0
	s_cmpk_gt_i32 s41, 0x147f
	v_cndmask_b32_e64 v33, 0, 1, s[4:5]
	s_cselect_b64 s[4:5], -1, 0
	v_readfirstlane_b32 s6, v32
	v_readfirstlane_b32 s7, v33
	s_cmp_lg_u64 s[4:5], 0
	s_addc_u32 s6, s6, s7
	s_cmpk_gt_i32 s41, 0x1b7f
	s_cselect_b64 s[4:5], -1, 0
	v_cndmask_b32_e64 v32, 0, 1, s[4:5]
	s_nop 0
	v_readfirstlane_b32 s4, v32
	s_add_u32 s6, s6, s4
	s_addc_u32 s7, 0, 0
	s_cmpk_gt_i32 s41, 0x1d7f
	s_cselect_b64 s[4:5], -1, 0
	v_cndmask_b32_e64 v32, 0, 1, s[4:5]
	s_nop 0
	v_readfirstlane_b32 s4, v32
	s_add_u32 s6, s6, s4
	s_addc_u32 s7, s7, 0
	s_cmpk_gt_i32 s41, 0x1f7f
	s_cselect_b64 s[4:5], -1, 0
	v_cndmask_b32_e64 v32, 0, 1, s[4:5]
	s_nop 0
	v_readfirstlane_b32 s4, v32
	s_add_u32 s6, s6, s4
	s_addc_u32 s7, s7, 0
	s_cmpk_gt_i32 s41, 0x217f
	s_cselect_b64 s[4:5], -1, 0
	v_cndmask_b32_e64 v32, 0, 1, s[4:5]
	s_nop 0
	v_readfirstlane_b32 s4, v32
	s_add_u32 s16, s6, s4
	s_addc_u32 s4, s7, 0
	s_mul_i32 s4, s4, 40
	s_mul_hi_u32 s5, s16, 40
	s_add_i32 s22, s5, s4
	s_mul_i32 s28, s16, 40
	s_getpc_b64 s[4:5]
	s_add_u32 s4, s4, _ZL5P0TAB@rel32@lo+4
	s_addc_u32 s5, s5, _ZL5P0TAB@rel32@hi+12
	s_add_u32 s38, s4, s28
	s_addc_u32 s39, s5, s22
	s_load_dword s10, s[38:39], 0x0
	s_waitcnt lgkmcnt(0)
	s_ashr_i32 s11, s10, 31
	s_getpc_b64 s[4:5]
	s_add_u32 s4, s4, _ZL5P0TAB@rel32@lo+12
	s_addc_u32 s5, s5, _ZL5P0TAB@rel32@hi+20
	s_add_u32 s8, s4, s28
	s_addc_u32 s9, s5, s22
	s_getpc_b64 s[26:27]
	s_add_u32 s26, s26, _ZL5P0TAB@rel32@lo+36
	s_addc_u32 s27, s27, _ZL5P0TAB@rel32@hi+44
	s_add_u32 s28, s26, s28
	s_load_dwordx4 s[4:7], s[8:9], 0x0
	s_addc_u32 s29, s27, s22
	s_lshl_b64 s[10:11], s[10:11], 3
	s_add_u32 s10, s0, s10
	s_addc_u32 s11, s1, s11
	s_lshl_b64 s[26:27], 1, s16
	s_and_b32 s22, s26, 0xa9
	s_cmp_eq_u64 s[22:23], 0
	s_mov_b64 s[26:27], 0
	s_cbranch_scc1 .LBB0_661
	s_load_dword s22, s[38:39], 0x4
	s_waitcnt lgkmcnt(0)
	s_lshl_b64 s[26:27], s[22:23], 3
	s_add_u32 s26, s0, s26
	s_addc_u32 s27, s1, s27
	s_load_dwordx2 s[26:27], s[26:27], 0x0
